# P8 prompt-row streaming loads (PR/AA/Y/GB/SG0/LO, dwordx2) carry the nt cache hint
# speedup vs baseline: 1.0080x; 1.0080x over previous
; __device__ __forceinline__ f32x4 unpack4(u32x2 u) { return (f32x4){__uint_as_float(u.x << 16), __uint_as_float(u.x & 0xffff0000u), __uint_as_float(u.y << 16), __uint_as_float(u.y & 0xffff0000u)}; }
; template <int ph>
; __device__ __forceinline__ void run_phase(const Args& args, LAS unsigned char* lds, const int G, const int bx, const bool fin = true) {
;     ...
;         for (int row = gw; row < MP; row += ngw) {
;             const int t = row & (T - 1); const int pbo = t > 0 ? -RP : 0; const float pm = t > 0 ? 1.f : 0.f;
;             POST_ROW(qr = unpack4(*(const u32x2*)(base + pbo)) * pm; qk = unpack4(*(const u32x2*)(base + pbo + 1024)) * pm; qv = unpack4(*(const u32x2*)(base + pbo + 2048)) * pm;)
.LBB0_1140:
	s_and_b32 s0, s42, 0x7ff
	v_lshl_add_u64 v[58:59], s[20:21], 0, v[56:57]
	s_cmp_eq_u32 s0, 0
	v_add_co_u32_e64 v90, s[0:1], s27, v58
	v_lshl_add_u64 v[64:65], s[24:25], 0, v[56:57]
	s_nop 0
	v_addc_co_u32_e64 v91, s[0:1], 0, v59, s[0:1]
	v_add_co_u32_e64 v86, s[0:1], s28, v58
	v_add_co_u32_e32 v60, vcc, 0x9e00000, v64
	s_nop 0
	v_addc_co_u32_e64 v87, s[0:1], 0, v59, s[0:1]
	v_add_co_u32_e64 v78, s[0:1], s38, v58
	v_addc_co_u32_e32 v61, vcc, 0, v65, vcc
	s_nop 0
	v_addc_co_u32_e64 v79, s[0:1], 0, v59, s[0:1]
	v_add_co_u32_e64 v80, s[0:1], s39, v58
	global_load_dwordx4 v[8:11], v[30:31], off
	global_load_dwordx4 v[12:15], v[32:33], off
	global_load_dwordx4 v[16:19], v[34:35], off
	v_addc_co_u32_e64 v81, s[0:1], 0, v59, s[0:1]
	v_add_co_u32_e64 v82, s[0:1], s40, v58
	global_load_dwordx4 v[24:27], v[36:37], off
	global_load_dwordx4 v[20:23], v[38:39], off
	global_load_dwordx4 v[0:3], v[40:41], off
	global_load_dwordx4 v[4:7], v[42:43], off
	v_addc_co_u32_e64 v83, s[0:1], 0, v59, s[0:1]
	v_add_co_u32_e64 v58, s[0:1], s41, v58
	global_load_dwordx2 v[76:77], v[90:91], off nt
	global_load_dwordx2 v[74:75], v[86:87], off nt
	global_load_dwordx2 v[72:73], v[78:79], off nt
	global_load_dwordx2 v[70:71], v[80:81], off nt
	global_load_dwordx2 v[68:69], v[82:83], off nt
	global_load_dwordx2 v[84:85], v[90:91], off offset:512 nt
	global_load_dwordx2 v[88:89], v[86:87], off offset:512 nt
	global_load_dwordx2 v[92:93], v[78:79], off offset:512 nt
	global_load_dwordx2 v[94:95], v[80:81], off offset:512 nt
	v_addc_co_u32_e64 v59, s[0:1], 0, v59, s[0:1]
	s_cselect_b64 s[0:1], -1, 0
	s_nop 0
	v_cndmask_b32_e64 v62, 1.0, 0, s[0:1]
	s_and_b64 s[0:1], s[0:1], exec
	global_load_dwordx2 v[96:97], v[82:83], off offset:512 nt
	global_load_dwordx2 v[98:99], v[90:91], off offset:1024 nt
	v_add_co_u32_e32 v66, vcc, s26, v64
	s_cselect_b32 s1, 0, -1
	s_cselect_b32 s0, 0, 0xffffe600
	global_load_dwordx2 v[112:113], v[90:91], off offset:1536 nt
	s_nop 0
	global_load_dwordx2 v[90:91], v[86:87], off offset:1024 nt
	s_nop 0
	global_load_dwordx2 v[86:87], v[86:87], off offset:1536 nt
	s_nop 0
	global_load_dwordx2 v[114:115], v[78:79], off offset:1024 nt
	global_load_dwordx2 v[134:135], v[78:79], off offset:1536 nt
	global_load_dwordx2 v[136:137], v[80:81], off offset:1024 nt
	global_load_dwordx2 v[140:141], v[80:81], off offset:1536 nt
	global_load_dwordx2 v[142:143], v[82:83], off offset:1024 nt
	global_load_dwordx2 v[144:145], v[82:83], off offset:1536 nt
	v_addc_co_u32_e32 v67, vcc, 0, v65, vcc
	v_lshl_add_u64 v[64:65], v[64:65], 0, s[0:1]
	v_add_co_u32_e32 v78, vcc, s19, v64
	global_load_dwordx2 v[146:147], v[60:61], off nt
	global_load_dwordx2 v[148:149], v[60:61], off offset:2048 nt
	v_addc_co_u32_e32 v79, vcc, 0, v65, vcc
	global_load_dwordx2 v[150:151], v[66:67], off nt
	global_load_dwordx2 v[152:153], v[78:79], off offset:2048 nt
	v_add_co_u32_e32 v80, vcc, s26, v64
	s_add_i32 s42, s42, s18
	s_nop 0
	v_addc_co_u32_e32 v81, vcc, 0, v65, vcc
	global_load_dwordx2 v[154:155], v[80:81], off offset:-4096 nt
	global_load_dwordx2 v[156:157], v[80:81], off nt
	s_add_u32 s20, s20, s22
	s_addc_u32 s21, s21, s23
	s_add_u32 s24, s24, s13
	s_addc_u32 s25, s25, s11
	s_cmpk_gt_i32 s42, 0x3fff
	s_waitcnt vmcnt(0)
	v_lshlrev_b32_e32 v160, 16, v77
	v_lshlrev_b32_e32 v129, 16, v75
	v_lshlrev_b32_e32 v128, 16, v74
	v_and_b32_e32 v163, 0xffff0000, v75
	v_and_b32_e32 v162, 0xffff0000, v74
	v_and_b32_e32 v161, 0xffff0000, v77
	v_lshlrev_b32_e32 v164, 16, v84
	v_and_b32_e32 v165, 0xffff0000, v84
	v_lshlrev_b32_e32 v131, 16, v89
	v_lshlrev_b32_e32 v130, 16, v88
	v_and_b32_e32 v167, 0xffff0000, v89
	v_and_b32_e32 v166, 0xffff0000, v88
	v_pk_add_f32 v[178:179], v[128:129], v[162:163]
	v_lshlrev_b32_e32 v133, 16, v91
	v_lshlrev_b32_e32 v108, 16, v96
	v_and_b32_e32 v109, 0xffff0000, v96
	v_lshlrev_b32_e32 v110, 16, v97
	v_and_b32_e32 v111, 0xffff0000, v97
	v_lshlrev_b32_e32 v168, 16, v98
	v_and_b32_e32 v169, 0xffff0000, v98
	v_lshlrev_b32_e32 v170, 16, v99
	v_and_b32_e32 v171, 0xffff0000, v99
	v_lshlrev_b32_e32 v132, 16, v90
	v_and_b32_e32 v173, 0xffff0000, v91
	v_and_b32_e32 v172, 0xffff0000, v90
	v_lshlrev_b32_e32 v96, 16, v142
	v_and_b32_e32 v97, 0xffff0000, v142
	v_lshlrev_b32_e32 v98, 16, v143
	v_and_b32_e32 v99, 0xffff0000, v143
	v_lshlrev_b32_e32 v142, 16, v112
	v_and_b32_e32 v143, 0xffff0000, v112
	v_lshlrev_b32_e32 v83, 16, v87
	v_lshlrev_b32_e32 v82, 16, v86
	v_and_b32_e32 v177, 0xffff0000, v87
	v_and_b32_e32 v176, 0xffff0000, v86
	v_lshlrev_b32_e32 v100, 16, v92
	v_and_b32_e32 v101, 0xffff0000, v92
	v_lshlrev_b32_e32 v104, 16, v93
	v_and_b32_e32 v105, 0xffff0000, v93
	v_lshlrev_b32_e32 v102, 16, v94
	v_and_b32_e32 v103, 0xffff0000, v94
	v_lshlrev_b32_e32 v106, 16, v95
	v_and_b32_e32 v107, 0xffff0000, v95
	v_lshlrev_b32_e32 v88, 16, v114
	v_and_b32_e32 v89, 0xffff0000, v114
	v_lshlrev_b32_e32 v92, 16, v115
	v_and_b32_e32 v93, 0xffff0000, v115
	v_lshlrev_b32_e32 v90, 16, v136
	v_and_b32_e32 v91, 0xffff0000, v136
	v_lshlrev_b32_e32 v94, 16, v137
	v_and_b32_e32 v95, 0xffff0000, v137
	v_pk_add_f32 v[160:161], v[160:161], -1.0 op_sel_hi:[1,0]
	v_pk_add_f32 v[136:137], v[164:165], -1.0 op_sel_hi:[1,0]
	v_pk_add_f32 v[164:165], v[130:131], v[166:167]
	v_pk_add_f32 v[114:115], v[168:169], -1.0 op_sel_hi:[1,0]
	v_pk_add_f32 v[168:169], v[132:133], v[172:173]
	v_pk_add_f32 v[86:87], v[142:143], -1.0 op_sel_hi:[1,0]
	v_pk_add_f32 v[142:143], v[82:83], v[176:177]
	v_add_f32_e32 v139, v178, v179
	v_pk_fma_f32 v[26:27], v[26:27], v[160:161], 1.0 op_sel_hi:[1,1,0]
	v_add_f32_e32 v160, v164, v165
	v_add_f32_e32 v161, v168, v169
	v_add_f32_e32 v164, v142, v143
	v_add_f32_dpp v139, v139, v139 quad_perm:[1,0,3,2] row_mask:0xf bank_mask:0xf bound_ctrl:1
	v_lshlrev_b32_e32 v158, 16, v76
	v_and_b32_e32 v159, 0xffff0000, v76
	v_lshlrev_b32_e32 v116, 16, v72
	v_and_b32_e32 v117, 0xffff0000, v72
	v_lshlrev_b32_e32 v120, 16, v73
	v_and_b32_e32 v121, 0xffff0000, v73
	v_lshlrev_b32_e32 v124, 16, v68
	v_and_b32_e32 v125, 0xffff0000, v68
	v_lshlrev_b32_e32 v126, 16, v69
	v_and_b32_e32 v127, 0xffff0000, v69
	v_lshlrev_b32_e32 v68, 16, v140
	v_and_b32_e32 v69, 0xffff0000, v140
	v_lshlrev_b32_e32 v72, 16, v141
	v_and_b32_e32 v73, 0xffff0000, v141
	v_lshlrev_b32_e32 v74, 16, v144
	v_and_b32_e32 v75, 0xffff0000, v144
	v_lshlrev_b32_e32 v76, 16, v145
	v_and_b32_e32 v77, 0xffff0000, v145
	v_lshlrev_b32_e32 v140, 16, v146
	v_and_b32_e32 v141, 0xffff0000, v146
	v_lshlrev_b32_e32 v144, 16, v147
	v_and_b32_e32 v145, 0xffff0000, v147
	v_lshlrev_b32_e32 v146, 16, v148
	v_and_b32_e32 v147, 0xffff0000, v148
	v_lshlrev_b32_e32 v148, 16, v149
	v_and_b32_e32 v149, 0xffff0000, v149
	v_add_f32_dpp v160, v160, v160 quad_perm:[1,0,3,2] row_mask:0xf bank_mask:0xf bound_ctrl:1
	v_add_f32_dpp v161, v161, v161 quad_perm:[1,0,3,2] row_mask:0xf bank_mask:0xf bound_ctrl:1
	v_add_f32_dpp v164, v164, v164 quad_perm:[1,0,3,2] row_mask:0xf bank_mask:0xf bound_ctrl:1
	v_add_f32_dpp v139, v139, v139 quad_perm:[2,3,0,1] row_mask:0xf bank_mask:0xf bound_ctrl:1
	v_lshlrev_b32_e32 v84, 16, v85
	v_and_b32_e32 v85, 0xffff0000, v85
	v_lshlrev_b32_e32 v174, 16, v113
	v_and_b32_e32 v175, 0xffff0000, v113
	v_xor_b32_e32 v183, 0x80000000, v149
	v_xor_b32_e32 v182, 0x80000000, v148
	v_xor_b32_e32 v185, 0x80000000, v147
	v_xor_b32_e32 v184, 0x80000000, v146
	v_add_f32_dpp v165, v160, v160 quad_perm:[2,3,0,1] row_mask:0xf bank_mask:0xf bound_ctrl:1
	v_add_f32_dpp v168, v161, v161 quad_perm:[2,3,0,1] row_mask:0xf bank_mask:0xf bound_ctrl:1
	v_add_f32_dpp v164, v164, v164 quad_perm:[2,3,0,1] row_mask:0xf bank_mask:0xf bound_ctrl:1
	v_lshlrev_b32_e32 v160, 16, v152
	v_and_b32_e32 v161, 0xffff0000, v152
	v_lshlrev_b32_e32 v152, 16, v153
	v_and_b32_e32 v153, 0xffff0000, v153
	v_add_f32_dpp v139, v139, v139 row_half_mirror row_mask:0xf bank_mask:0xf bound_ctrl:1
	v_lshlrev_b32_e32 v118, 16, v70
	v_and_b32_e32 v119, 0xffff0000, v70
	v_lshlrev_b32_e32 v122, 16, v71
	v_and_b32_e32 v123, 0xffff0000, v71
	v_lshlrev_b32_e32 v64, 16, v134
	v_and_b32_e32 v65, 0xffff0000, v134
	v_lshlrev_b32_e32 v70, 16, v135
	v_and_b32_e32 v71, 0xffff0000, v135
	v_pk_add_f32 v[158:159], v[158:159], -1.0 op_sel_hi:[1,0]
	v_pk_add_f32 v[134:135], v[84:85], -1.0 op_sel_hi:[1,0]
	v_pk_add_f32 v[112:113], v[170:171], -1.0 op_sel_hi:[1,0]
	v_pk_add_f32 v[84:85], v[174:175], -1.0 op_sel_hi:[1,0]
	v_lshlrev_b32_e32 v170, 16, v150
	v_and_b32_e32 v171, 0xffff0000, v150
	v_lshlrev_b32_e32 v150, 16, v151
	v_and_b32_e32 v151, 0xffff0000, v151
	v_xor_b32_e32 v175, 0x80000000, v141
	v_xor_b32_e32 v174, 0x80000000, v140
	v_xor_b32_e32 v181, 0x80000000, v145
	v_xor_b32_e32 v180, 0x80000000, v144
	v_add_f32_dpp v178, v165, v165 row_half_mirror row_mask:0xf bank_mask:0xf bound_ctrl:1
	v_add_f32_dpp v179, v168, v168 row_half_mirror row_mask:0xf bank_mask:0xf bound_ctrl:1
	v_add_f32_dpp v186, v164, v164 row_half_mirror row_mask:0xf bank_mask:0xf bound_ctrl:1
	v_lshlrev_b32_e32 v164, 16, v154
	v_and_b32_e32 v165, 0xffff0000, v154
	v_lshlrev_b32_e32 v154, 16, v155
	v_and_b32_e32 v155, 0xffff0000, v155
	v_pk_fma_f32 v[152:153], v[62:63], v[152:153], v[182:183] op_sel_hi:[0,1,1]
	v_pk_fma_f32 v[160:161], v[62:63], v[160:161], v[184:185] op_sel_hi:[0,1,1]
	v_add_f32_dpp v139, v139, v139 row_mirror row_mask:0xf bank_mask:0xf bound_ctrl:1
	v_pk_fma_f32 v[24:25], v[24:25], v[158:159], 1.0 op_sel_hi:[1,1,0]
	v_xor_b32_e32 v143, 0x80000000, v151
	v_xor_b32_e32 v142, 0x80000000, v150
	v_lshlrev_b32_e32 v168, 16, v156
	v_and_b32_e32 v169, 0xffff0000, v156
	v_lshlrev_b32_e32 v156, 16, v157
	v_and_b32_e32 v157, 0xffff0000, v157
	v_add_f32_dpp v178, v178, v178 row_mirror row_mask:0xf bank_mask:0xf bound_ctrl:1
	v_add_f32_dpp v179, v179, v179 row_mirror row_mask:0xf bank_mask:0xf bound_ctrl:1
	v_pk_fma_f32 v[164:165], v[62:63], v[164:165], v[174:175] op_sel_hi:[0,1,1]
	v_pk_fma_f32 v[154:155], v[62:63], v[154:155], v[180:181] op_sel_hi:[0,1,1]
	v_pk_fma_f32 v[12:13], v[12:13], v[160:161], v[146:147]
	v_pk_fma_f32 v[14:15], v[14:15], v[152:153], v[148:149]
	v_fmac_f32_e32 v162, 0xbc800000, v139
	v_fmac_f32_e32 v163, 0xbc800000, v139
	v_fmac_f32_e32 v129, 0xbc800000, v139
	v_xor_b32_e32 v159, 0x80000000, v171
	v_xor_b32_e32 v158, 0x80000000, v170
	v_pk_fma_f32 v[142:143], v[62:63], v[156:157], v[142:143] op_sel_hi:[0,1,1]
	v_fmac_f32_e32 v128, 0xbc800000, v139
	v_fmac_f32_e32 v166, 0xbc800000, v178
	v_fmac_f32_e32 v167, 0xbc800000, v178
	v_fmac_f32_e32 v131, 0xbc800000, v178
	v_fmac_f32_e32 v172, 0xbc800000, v179
	v_fmac_f32_e32 v173, 0xbc800000, v179
	v_fmac_f32_e32 v133, 0xbc800000, v179
	v_pk_fma_f32 v[10:11], v[10:11], v[154:155], v[144:145]
	v_pk_fma_f32 v[140:141], v[8:9], v[164:165], v[140:141]
	v_pk_mul_f32 v[14:15], v[14:15], v[26:27]
	v_pk_mul_f32 v[12:13], v[12:13], v[24:25]
	v_mov_b32_e32 v24, v129
	v_mov_b32_e32 v25, v163
	v_mov_b32_e32 v129, v162
	v_add_f32_dpp v182, v186, v186 row_mirror row_mask:0xf bank_mask:0xf bound_ctrl:1
	v_pk_fma_f32 v[146:147], v[62:63], v[168:169], v[158:159] op_sel_hi:[0,1,1]
	v_fmac_f32_e32 v130, 0xbc800000, v178
	v_fmac_f32_e32 v132, 0xbc800000, v179
	v_pk_fma_f32 v[18:19], v[18:19], v[142:143], v[150:151]
	v_mov_b32_e32 v26, v131
	v_mov_b32_e32 v27, v167
	v_mov_b32_e32 v131, v166
	v_mov_b32_e32 v142, v133
	v_mov_b32_e32 v143, v173
	v_mov_b32_e32 v133, v172
	v_pk_mul_f32 v[12:13], v[140:141], v[12:13]
	v_pk_mul_f32 v[10:11], v[10:11], v[14:15]
	v_pk_mul_f32 v[14:15], v[24:25], v[24:25]
	v_pk_mul_f32 v[140:141], v[128:129], v[128:129]
	v_fmac_f32_e32 v176, 0xbc800000, v182
	v_fmac_f32_e32 v177, 0xbc800000, v182
	v_fmac_f32_e32 v83, 0xbc800000, v182
	v_pk_fma_f32 v[16:17], v[16:17], v[146:147], v[170:171]
	v_pk_mul_f32 v[144:145], v[26:27], v[26:27]
	v_pk_mul_f32 v[146:147], v[130:131], v[130:131]
	v_pk_mul_f32 v[148:149], v[142:143], v[142:143]
	v_pk_mul_f32 v[150:151], v[132:133], v[132:133]
	v_pk_mul_f32 v[10:11], v[22:23], v[10:11]
	v_pk_mul_f32 v[12:13], v[20:21], v[12:13]
	v_pk_mov_b32 v[20:21], v[140:141], v[14:15] op_sel:[1,0]
	v_mov_b32_e32 v141, v15
	v_fmac_f32_e32 v82, 0xbc800000, v182
	v_mov_b32_e32 v8, v83
	v_mov_b32_e32 v9, v177
	v_mov_b32_e32 v83, v176
	v_pk_mov_b32 v[14:15], v[146:147], v[144:145] op_sel:[1,0]
	v_mov_b32_e32 v147, v145
	v_pk_mov_b32 v[22:23], v[150:151], v[148:149] op_sel:[1,0]
	v_mov_b32_e32 v151, v149
	v_pk_mov_b32 v[148:149], v[12:13], v[10:11] op_sel:[1,0]
	v_mov_b32_e32 v13, v11
	v_pk_add_f32 v[10:11], v[20:21], v[140:141]
	v_pk_mul_f32 v[152:153], v[8:9], v[8:9]
	v_pk_mul_f32 v[154:155], v[82:83], v[82:83]
	v_pk_add_f32 v[14:15], v[14:15], v[146:147]
	v_pk_add_f32 v[20:21], v[22:23], v[150:151]
	v_pk_add_f32 v[12:13], v[148:149], v[12:13]
	v_add_f32_e32 v10, v10, v11
	v_pk_mov_b32 v[144:145], v[154:155], v[152:153] op_sel:[1,0]
	v_mov_b32_e32 v155, v153
	v_add_f32_e32 v11, v14, v15
	v_add_f32_e32 v14, v20, v21
	v_add_f32_e32 v12, v12, v13
	v_add_f32_dpp v10, v10, v10 quad_perm:[1,0,3,2] row_mask:0xf bank_mask:0xf bound_ctrl:1
	v_pk_add_f32 v[22:23], v[144:145], v[154:155]
	v_add_f32_dpp v13, v14, v14 quad_perm:[1,0,3,2] row_mask:0xf bank_mask:0xf bound_ctrl:1
	v_add_f32_dpp v12, v12, v12 quad_perm:[1,0,3,2] row_mask:0xf bank_mask:0xf bound_ctrl:1
	v_add_f32_dpp v10, v10, v10 quad_perm:[2,3,0,1] row_mask:0xf bank_mask:0xf bound_ctrl:1
	v_add_f32_e32 v15, v22, v23
	v_add_f32_dpp v11, v11, v11 quad_perm:[1,0,3,2] row_mask:0xf bank_mask:0xf bound_ctrl:1
	v_add_f32_dpp v13, v13, v13 quad_perm:[2,3,0,1] row_mask:0xf bank_mask:0xf bound_ctrl:1
	v_add_f32_dpp v12, v12, v12 quad_perm:[2,3,0,1] row_mask:0xf bank_mask:0xf bound_ctrl:1
	v_add_f32_dpp v10, v10, v10 row_half_mirror row_mask:0xf bank_mask:0xf bound_ctrl:1
	v_add_f32_dpp v14, v15, v15 quad_perm:[1,0,3,2] row_mask:0xf bank_mask:0xf bound_ctrl:1
	v_add_f32_dpp v11, v11, v11 quad_perm:[2,3,0,1] row_mask:0xf bank_mask:0xf bound_ctrl:1
	v_add_f32_dpp v13, v13, v13 row_half_mirror row_mask:0xf bank_mask:0xf bound_ctrl:1
	v_add_f32_dpp v12, v12, v12 row_half_mirror row_mask:0xf bank_mask:0xf bound_ctrl:1
	v_add_f32_dpp v15, v10, v10 row_mirror row_mask:0xf bank_mask:0xf bound_ctrl:1
	v_add_f32_dpp v11, v11, v11 row_half_mirror row_mask:0xf bank_mask:0xf bound_ctrl:1
	v_add_f32_dpp v13, v13, v13 row_mirror row_mask:0xf bank_mask:0xf bound_ctrl:1
	v_add_f32_dpp v10, v12, v12 row_mirror row_mask:0xf bank_mask:0xf bound_ctrl:1
	v_fmamk_f32 v12, v15, 0x3c800000, v29
	v_add_f32_dpp v14, v14, v14 quad_perm:[2,3,0,1] row_mask:0xf bank_mask:0xf bound_ctrl:1
	v_add_f32_dpp v11, v11, v11 row_mirror row_mask:0xf bank_mask:0xf bound_ctrl:1
	v_fmamk_f32 v13, v13, 0x3c800000, v29
	v_mul_f32_e32 v15, 0x4f800000, v12
	v_cmp_gt_f32_e64 s[4:5], s29, v12
	v_add_f32_dpp v14, v14, v14 row_half_mirror row_mask:0xf bank_mask:0xf bound_ctrl:1
	v_fmamk_f32 v11, v11, 0x3c800000, v29
	v_mul_f32_e32 v21, 0x4f800000, v13
	v_cmp_gt_f32_e64 s[0:1], s29, v13
	v_cndmask_b32_e64 v12, v12, v15, s[4:5]
	v_add_f32_dpp v14, v14, v14 row_mirror row_mask:0xf bank_mask:0xf bound_ctrl:1
	v_mul_f32_e32 v20, 0x4f800000, v11
	v_cmp_gt_f32_e32 vcc, s29, v11
	v_cndmask_b32_e64 v13, v13, v21, s[0:1]
	v_sqrt_f32_e32 v15, v12
	v_fmamk_f32 v14, v14, 0x3c800000, v29
	v_cndmask_b32_e32 v11, v11, v20, vcc
	v_sqrt_f32_e32 v21, v13
	v_mul_f32_e32 v22, 0x4f800000, v14
	v_cmp_gt_f32_e64 s[2:3], s29, v14
	v_sqrt_f32_e32 v20, v11
	v_add_u32_e32 v23, -1, v15
	v_cndmask_b32_e64 v14, v14, v22, s[2:3]
	v_sqrt_f32_e32 v22, v14
	v_add_u32_e32 v139, 1, v15
	v_add_u32_e32 v144, -1, v21
	v_fma_f32 v148, -v23, v15, v12
	v_add_u32_e32 v140, -1, v20
	v_add_u32_e32 v145, 1, v21
	v_fma_f32 v149, -v139, v15, v12
	v_fma_f32 v152, -v144, v21, v13
	v_cmp_ge_f32_e64 s[6:7], 0, v148
	v_add_u32_e32 v141, 1, v20
	v_fma_f32 v150, -v140, v20, v11
	v_fma_f32 v153, -v145, v21, v13
	v_cndmask_b32_e64 v15, v15, v23, s[6:7]
	v_cmp_ge_f32_e64 s[8:9], 0, v152
	v_cmp_lt_f32_e64 s[16:17], 0, v149
	v_add_u32_e32 v146, -1, v22
	v_fma_f32 v151, -v141, v20, v11
	v_cmp_ge_f32_e64 s[6:7], 0, v150
	v_cndmask_b32_e64 v21, v21, v144, s[8:9]
	v_cmp_lt_f32_e64 s[8:9], 0, v153
	v_cndmask_b32_e64 v15, v15, v139, s[16:17]
	v_add_u32_e32 v147, 1, v22
	v_fma_f32 v154, -v146, v22, v14
	v_cndmask_b32_e64 v20, v20, v140, s[6:7]
	v_cmp_lt_f32_e64 s[6:7], 0, v151
	v_cndmask_b32_e64 v21, v21, v145, s[8:9]
	v_mul_f32_e32 v23, 0x37800000, v15
	v_fma_f32 v155, -v147, v22, v14
	v_cmp_ge_f32_e64 s[14:15], 0, v154
	v_cndmask_b32_e64 v20, v20, v141, s[6:7]
	v_mul_f32_e32 v140, 0x37800000, v21
	v_cndmask_b32_e64 v15, v15, v23, s[4:5]
	v_cmp_class_f32_e64 s[4:5], v12, v138
	v_cndmask_b32_e64 v22, v22, v146, s[14:15]
	v_cmp_lt_f32_e64 s[14:15], 0, v155
	v_mul_f32_e32 v139, 0x37800000, v20
	v_cndmask_b32_e64 v21, v21, v140, s[0:1]
	v_cmp_class_f32_e64 s[0:1], v13, v138
	v_cndmask_b32_e64 v12, v15, v12, s[4:5]
	v_cndmask_b32_e64 v22, v22, v147, s[14:15]
	v_cndmask_b32_e32 v20, v20, v139, vcc
	v_cmp_class_f32_e32 vcc, v11, v138
	v_cndmask_b32_e64 v21, v21, v13, s[0:1]
	v_div_scale_f32 v13, s[0:1], v12, v12, 1.0
	v_mul_f32_e32 v141, 0x37800000, v22
	v_cndmask_b32_e32 v11, v20, v11, vcc
	v_rcp_f32_e32 v140, v13
	v_cndmask_b32_e64 v22, v22, v141, s[2:3]
	v_cmp_class_f32_e64 s[2:3], v14, v138
	v_div_scale_f32 v15, s[0:1], v11, v11, 1.0
	s_nop 0
	v_cndmask_b32_e64 v139, v22, v14, s[2:3]
	v_div_scale_f32 v22, s[2:3], v21, v21, 1.0
	v_rcp_f32_e32 v141, v15
	v_rcp_f32_e32 v144, v22
	v_fma_f32 v145, -v13, v140, 1.0
	v_div_scale_f32 v14, vcc, 1.0, v12, 1.0
	v_fmac_f32_e32 v140, v145, v140
	v_fma_f32 v146, -v15, v141, 1.0
	v_mul_f32_e32 v145, v14, v140
	v_div_scale_f32 v20, s[0:1], 1.0, v11, 1.0
	v_fma_f32 v147, -v22, v144, 1.0
	v_fmac_f32_e32 v141, v146, v141
	v_fma_f32 v148, -v13, v145, v14
	v_div_scale_f32 v23, s[4:5], 1.0, v21, 1.0
	v_fmac_f32_e32 v144, v147, v144
	v_mul_f32_e32 v146, v20, v141
	v_fmac_f32_e32 v145, v148, v140
	v_mul_f32_e32 v147, v23, v144
	v_fma_f32 v149, -v15, v146, v20
	v_fma_f32 v13, -v13, v145, v14
	v_fma_f32 v150, -v22, v147, v23
	v_fmac_f32_e32 v146, v149, v141
	v_div_fmas_f32 v13, v13, v140, v145
	v_fmac_f32_e32 v147, v150, v144
	v_fma_f32 v14, -v15, v146, v20
	v_div_fixup_f32 v12, v13, v12, 1.0
	s_mov_b64 vcc, s[0:1]
	v_fma_f32 v22, -v22, v147, v23
	v_div_fmas_f32 v20, v14, v141, v146
	v_pk_mul_f32 v[14:15], v[24:25], v[12:13] op_sel_hi:[1,0]
	v_pk_mul_f32 v[12:13], v[128:129], v[12:13] op_sel_hi:[1,0]
	s_mov_b64 vcc, s[4:5]
	v_div_fixup_f32 v20, v20, v11, 1.0
	v_div_fmas_f32 v11, v22, v144, v147
	v_pk_fma_f32 v[0:1], v[0:1], v[12:13], v[4:5]
	v_pk_fma_f32 v[2:3], v[2:3], v[14:15], v[6:7]
	v_pk_fma_f32 v[0:1], v[16:17], v[10:11], v[0:1] op_sel_hi:[1,0,1]
	v_pk_fma_f32 v[2:3], v[18:19], v[10:11], v[2:3] op_sel_hi:[1,0,1]
	v_pk_mul_f32 v[0:1], v[0:1], v[116:117]
	v_pk_mul_f32 v[2:3], v[2:3], v[120:121]
	v_pk_fma_f32 v[0:1], v[0:1], v[118:119], v[124:125]
	v_pk_fma_f32 v[2:3], v[2:3], v[122:123], v[126:127]
	v_cvt_pk_bf16_f32 v0, v0, v1
	v_cvt_pk_bf16_f32 v1, v2, v3
	v_div_fixup_f32 v4, v11, v21, 1.0
	global_store_dwordx2 v[58:59], v[0:1], off
	v_pk_mul_f32 v[26:27], v[26:27], v[20:21] op_sel_hi:[1,0]
	v_pk_mul_f32 v[128:129], v[130:131], v[20:21] op_sel_hi:[1,0]
	v_pk_mul_f32 v[130:131], v[142:143], v[4:5] op_sel_hi:[1,0]
	v_pk_mul_f32 v[132:133], v[132:133], v[4:5] op_sel_hi:[1,0]
	global_load_dwordx2 v[120:121], v[60:61], off offset:512 nt
	global_load_dwordx2 v[122:123], v[60:61], off offset:2560 nt
	global_load_dwordx2 v[124:125], v[66:67], off offset:512 nt
	global_load_dwordx2 v[126:127], v[78:79], off offset:512 nt
	global_load_dwordx2 v[140:141], v[78:79], off offset:2560 nt
	global_load_dwordx2 v[142:143], v[80:81], off offset:512 nt
	global_load_dwordx4 v[0:3], v[36:37], off offset:1024
	global_load_dwordx4 v[4:7], v[40:41], off offset:1024
	global_load_dwordx4 v[10:13], v[42:43], off offset:1024
	global_load_dwordx4 v[14:17], v[30:31], off offset:1024
	global_load_dwordx4 v[18:21], v[44:45], off
	global_load_dwordx4 v[22:25], v[46:47], off
	global_load_dwordx4 v[116:119], v[38:39], off offset:1024
	v_div_scale_f32 v156, s[2:3], v139, v139, 1.0
	v_rcp_f32_e32 v158, v156
	v_div_scale_f32 v157, s[2:3], 1.0, v139, 1.0
	s_mov_b64 vcc, s[2:3]
	v_fma_f32 v159, -v156, v158, 1.0
	v_fmac_f32_e32 v158, v159, v158
	s_waitcnt vmcnt(12)
	v_lshlrev_b32_e32 v144, 16, v120
	v_and_b32_e32 v145, 0xffff0000, v120
	v_lshlrev_b32_e32 v120, 16, v121
	v_and_b32_e32 v121, 0xffff0000, v121
	s_waitcnt vmcnt(11)
	v_lshlrev_b32_e32 v146, 16, v122
	v_and_b32_e32 v147, 0xffff0000, v122
	v_lshlrev_b32_e32 v122, 16, v123
	v_and_b32_e32 v123, 0xffff0000, v123
	s_waitcnt vmcnt(9)
	v_lshlrev_b32_e32 v150, 16, v126
	v_and_b32_e32 v151, 0xffff0000, v126
	v_lshlrev_b32_e32 v126, 16, v127
	v_and_b32_e32 v127, 0xffff0000, v127
	s_waitcnt vmcnt(8)
	v_lshlrev_b32_e32 v152, 16, v140
	v_and_b32_e32 v153, 0xffff0000, v140
	v_lshlrev_b32_e32 v140, 16, v141
	v_and_b32_e32 v141, 0xffff0000, v141
	s_waitcnt vmcnt(4)
	v_pk_fma_f32 v[4:5], v[4:5], v[128:129], v[10:11]
	v_pk_fma_f32 v[6:7], v[6:7], v[26:27], v[12:13]
	v_xor_b32_e32 v11, 0x80000000, v145
	v_xor_b32_e32 v10, 0x80000000, v144
	v_xor_b32_e32 v13, 0x80000000, v121
	v_xor_b32_e32 v12, 0x80000000, v120
	v_xor_b32_e32 v27, 0x80000000, v123
	v_xor_b32_e32 v26, 0x80000000, v122
	v_xor_b32_e32 v129, 0x80000000, v147
	v_xor_b32_e32 v128, 0x80000000, v146
	v_pk_fma_f32 v[10:11], v[62:63], v[150:151], v[10:11] op_sel_hi:[0,1,1]
	v_pk_fma_f32 v[12:13], v[62:63], v[126:127], v[12:13] op_sel_hi:[0,1,1]
	v_pk_fma_f32 v[26:27], v[62:63], v[140:141], v[26:27] op_sel_hi:[0,1,1]
	v_pk_fma_f32 v[126:127], v[62:63], v[152:153], v[128:129] op_sel_hi:[0,1,1]
	v_pk_fma_f32 v[0:1], v[0:1], v[136:137], 1.0 op_sel_hi:[1,1,0]
	v_pk_fma_f32 v[2:3], v[2:3], v[134:135], 1.0 op_sel_hi:[1,1,0]
	s_waitcnt vmcnt(3)
	v_pk_fma_f32 v[12:13], v[16:17], v[12:13], v[120:121]
	v_pk_fma_f32 v[10:11], v[14:15], v[10:11], v[144:145]
	s_waitcnt vmcnt(2)
	v_pk_fma_f32 v[14:15], v[18:19], v[126:127], v[146:147]
	v_pk_fma_f32 v[16:17], v[20:21], v[26:27], v[122:123]
	v_pk_mul_f32 v[0:1], v[14:15], v[0:1]
	v_pk_mul_f32 v[2:3], v[16:17], v[2:3]
	v_pk_mul_f32 v[0:1], v[10:11], v[0:1]
	v_pk_mul_f32 v[2:3], v[12:13], v[2:3]
	s_waitcnt vmcnt(0)
	v_pk_mul_f32 v[0:1], v[116:117], v[0:1]
	v_pk_mul_f32 v[2:3], v[118:119], v[2:3]
	v_lshlrev_b32_e32 v148, 16, v124
	v_pk_mov_b32 v[10:11], v[0:1], v[2:3] op_sel:[1,0]
	v_mov_b32_e32 v1, v3
	v_pk_add_f32 v[0:1], v[10:11], v[0:1]
	v_and_b32_e32 v149, 0xffff0000, v124
	v_add_f32_e32 v0, v0, v1
	v_lshlrev_b32_e32 v124, 16, v125
	v_and_b32_e32 v125, 0xffff0000, v125
	v_add_f32_dpp v0, v0, v0 quad_perm:[1,0,3,2] row_mask:0xf bank_mask:0xf bound_ctrl:1
	v_lshlrev_b32_e32 v154, 16, v142
	v_and_b32_e32 v155, 0xffff0000, v142
	v_lshlrev_b32_e32 v142, 16, v143
	v_and_b32_e32 v143, 0xffff0000, v143
	v_xor_b32_e32 v135, 0x80000000, v125
	v_xor_b32_e32 v134, 0x80000000, v124
	v_xor_b32_e32 v137, 0x80000000, v149
	v_xor_b32_e32 v136, 0x80000000, v148
	v_add_f32_dpp v0, v0, v0 quad_perm:[2,3,0,1] row_mask:0xf bank_mask:0xf bound_ctrl:1
	v_pk_fma_f32 v[128:129], v[62:63], v[142:143], v[134:135] op_sel_hi:[0,1,1]
	v_pk_fma_f32 v[134:135], v[62:63], v[154:155], v[136:137] op_sel_hi:[0,1,1]
	v_add_f32_dpp v0, v0, v0 row_half_mirror row_mask:0xf bank_mask:0xf bound_ctrl:1
	v_pk_fma_f32 v[18:19], v[22:23], v[134:135], v[148:149]
	v_pk_fma_f32 v[20:21], v[24:25], v[128:129], v[124:125]
	v_add_f32_dpp v0, v0, v0 row_mirror row_mask:0xf bank_mask:0xf bound_ctrl:1
	v_pk_fma_f32 v[2:3], v[20:21], v[0:1], v[6:7] op_sel_hi:[1,0,1]
	v_pk_fma_f32 v[0:1], v[18:19], v[0:1], v[4:5] op_sel_hi:[1,0,1]
	v_pk_mul_f32 v[2:3], v[2:3], v[104:105]
	v_pk_mul_f32 v[0:1], v[0:1], v[100:101]
	v_pk_fma_f32 v[2:3], v[2:3], v[106:107], v[110:111]
	v_pk_fma_f32 v[0:1], v[0:1], v[102:103], v[108:109]
	s_nop 0
	v_cvt_pk_bf16_f32 v0, v0, v1
	v_cvt_pk_bf16_f32 v1, v2, v3
	global_store_dwordx2 v[58:59], v[0:1], off offset:512
	global_load_dwordx2 v[26:27], v[60:61], off offset:1024 nt
	global_load_dwordx2 v[104:105], v[60:61], off offset:3072 nt
	global_load_dwordx2 v[106:107], v[66:67], off offset:1024 nt
	global_load_dwordx2 v[108:109], v[78:79], off offset:1024 nt
	global_load_dwordx2 v[110:111], v[78:79], off offset:3072 nt
	global_load_dwordx2 v[116:117], v[80:81], off offset:1024 nt
	global_load_dwordx4 v[0:3], v[36:37], off offset:2048
	global_load_dwordx4 v[4:7], v[40:41], off offset:2048
	global_load_dwordx4 v[10:13], v[42:43], off offset:2048
	global_load_dwordx4 v[14:17], v[30:31], off offset:2048
	global_load_dwordx4 v[18:21], v[48:49], off
	global_load_dwordx4 v[22:25], v[50:51], off
	global_load_dwordx4 v[100:103], v[38:39], off offset:2048
	s_waitcnt vmcnt(12)
	v_lshlrev_b32_e32 v118, 16, v26
	v_and_b32_e32 v119, 0xffff0000, v26
	v_lshlrev_b32_e32 v26, 16, v27
	v_and_b32_e32 v27, 0xffff0000, v27
	s_waitcnt vmcnt(11)
	v_lshlrev_b32_e32 v120, 16, v104
	v_and_b32_e32 v121, 0xffff0000, v104
	v_lshlrev_b32_e32 v104, 16, v105
	v_and_b32_e32 v105, 0xffff0000, v105
	s_waitcnt vmcnt(9)
	v_lshlrev_b32_e32 v124, 16, v108
	v_and_b32_e32 v125, 0xffff0000, v108
	v_lshlrev_b32_e32 v108, 16, v109
	v_and_b32_e32 v109, 0xffff0000, v109
	s_waitcnt vmcnt(8)
	v_lshlrev_b32_e32 v126, 16, v110
	v_and_b32_e32 v127, 0xffff0000, v110
	v_lshlrev_b32_e32 v110, 16, v111
	v_and_b32_e32 v111, 0xffff0000, v111
	s_waitcnt vmcnt(6)
	v_pk_fma_f32 v[0:1], v[0:1], v[114:115], 1.0 op_sel_hi:[1,1,0]
	v_pk_fma_f32 v[2:3], v[2:3], v[112:113], 1.0 op_sel_hi:[1,1,0]
	s_waitcnt vmcnt(4)
	v_pk_fma_f32 v[4:5], v[4:5], v[132:133], v[10:11]
	v_pk_fma_f32 v[6:7], v[6:7], v[130:131], v[12:13]
	v_xor_b32_e32 v11, 0x80000000, v119
	v_xor_b32_e32 v10, 0x80000000, v118
	v_xor_b32_e32 v13, 0x80000000, v27
	v_xor_b32_e32 v12, 0x80000000, v26
	v_xor_b32_e32 v113, 0x80000000, v105
	v_xor_b32_e32 v112, 0x80000000, v104
	v_xor_b32_e32 v115, 0x80000000, v121
	v_xor_b32_e32 v114, 0x80000000, v120
	v_pk_fma_f32 v[10:11], v[62:63], v[124:125], v[10:11] op_sel_hi:[0,1,1]
	v_pk_fma_f32 v[12:13], v[62:63], v[108:109], v[12:13] op_sel_hi:[0,1,1]
	v_pk_fma_f32 v[108:109], v[62:63], v[110:111], v[112:113] op_sel_hi:[0,1,1]
	v_pk_fma_f32 v[110:111], v[62:63], v[126:127], v[114:115] op_sel_hi:[0,1,1]
	s_waitcnt vmcnt(3)
	v_pk_fma_f32 v[12:13], v[16:17], v[12:13], v[26:27]
	v_pk_fma_f32 v[10:11], v[14:15], v[10:11], v[118:119]
	s_waitcnt vmcnt(2)
	v_pk_fma_f32 v[14:15], v[18:19], v[110:111], v[120:121]
	v_pk_fma_f32 v[16:17], v[20:21], v[108:109], v[104:105]
	v_pk_mul_f32 v[0:1], v[14:15], v[0:1]
	v_pk_mul_f32 v[2:3], v[16:17], v[2:3]
	v_pk_mul_f32 v[0:1], v[10:11], v[0:1]
	v_pk_mul_f32 v[2:3], v[12:13], v[2:3]
	s_waitcnt vmcnt(0)
; __device__ __forceinline__ f32x4 unpack4(u32x2 u) { return (f32x4){__uint_as_float(u.x << 16), __uint_as_float(u.x & 0xffff0000u), __uint_as_float(u.y << 16), __uint_as_float(u.y & 0xffff0000u)}; }
; template <int ph>
; __device__ __forceinline__ void run_phase(const Args& args, LAS unsigned char* lds, const int G, const int bx, const bool fin = true) {
;     ...
;         for (int row = gw; row < MP; row += ngw) {
;             const int t = row & (T - 1); const int pbo = t > 0 ? -RP : 0; const float pm = t > 0 ? 1.f : 0.f;
;             POST_ROW(qr = unpack4(*(const u32x2*)(base + pbo)) * pm; qk = unpack4(*(const u32x2*)(base + pbo + 1024)) * pm; qv = unpack4(*(const u32x2*)(base + pbo + 2048)) * pm;)
	v_pk_mul_f32 v[0:1], v[100:101], v[0:1]
	v_pk_mul_f32 v[2:3], v[102:103], v[2:3]
	v_lshlrev_b32_e32 v122, 16, v106
	v_pk_mov_b32 v[10:11], v[0:1], v[2:3] op_sel:[1,0]
	v_mov_b32_e32 v1, v3
	v_pk_add_f32 v[0:1], v[10:11], v[0:1]
	v_and_b32_e32 v123, 0xffff0000, v106
	v_add_f32_e32 v0, v0, v1
	v_lshlrev_b32_e32 v106, 16, v107
	v_and_b32_e32 v107, 0xffff0000, v107
	v_add_f32_dpp v0, v0, v0 quad_perm:[1,0,3,2] row_mask:0xf bank_mask:0xf bound_ctrl:1
	v_lshlrev_b32_e32 v128, 16, v116
	v_and_b32_e32 v129, 0xffff0000, v116
	v_lshlrev_b32_e32 v116, 16, v117
	v_and_b32_e32 v117, 0xffff0000, v117
	v_xor_b32_e32 v131, 0x80000000, v107
	v_xor_b32_e32 v130, 0x80000000, v106
	v_xor_b32_e32 v133, 0x80000000, v123
	v_xor_b32_e32 v132, 0x80000000, v122
	v_add_f32_dpp v0, v0, v0 quad_perm:[2,3,0,1] row_mask:0xf bank_mask:0xf bound_ctrl:1
	v_pk_fma_f32 v[112:113], v[62:63], v[116:117], v[130:131] op_sel_hi:[0,1,1]
	v_pk_fma_f32 v[114:115], v[62:63], v[128:129], v[132:133] op_sel_hi:[0,1,1]
	v_add_f32_dpp v0, v0, v0 row_half_mirror row_mask:0xf bank_mask:0xf bound_ctrl:1
	v_pk_fma_f32 v[18:19], v[22:23], v[114:115], v[122:123]
	v_pk_fma_f32 v[20:21], v[24:25], v[112:113], v[106:107]
	v_add_f32_dpp v0, v0, v0 row_mirror row_mask:0xf bank_mask:0xf bound_ctrl:1
	v_pk_fma_f32 v[2:3], v[20:21], v[0:1], v[6:7] op_sel_hi:[1,0,1]
	v_pk_fma_f32 v[0:1], v[18:19], v[0:1], v[4:5] op_sel_hi:[1,0,1]
	v_pk_mul_f32 v[2:3], v[2:3], v[92:93]
	v_pk_mul_f32 v[0:1], v[0:1], v[88:89]
	v_pk_fma_f32 v[2:3], v[2:3], v[94:95], v[98:99]
	v_pk_fma_f32 v[0:1], v[0:1], v[90:91], v[96:97]
	v_mul_f32_e32 v94, v157, v158
	v_cvt_pk_bf16_f32 v0, v0, v1
	v_cvt_pk_bf16_f32 v1, v2, v3
	global_store_dwordx2 v[58:59], v[0:1], off offset:1024
	global_load_dwordx2 v[26:27], v[60:61], off offset:1536 nt
	s_nop 0
	global_load_dwordx2 v[60:61], v[60:61], off offset:3584 nt
	s_nop 0
	global_load_dwordx2 v[66:67], v[66:67], off offset:1536 nt
	s_nop 0
	global_load_dwordx2 v[88:89], v[78:79], off offset:1536 nt
	global_load_dwordx2 v[90:91], v[78:79], off offset:3584 nt
	global_load_dwordx2 v[92:93], v[80:81], off offset:1536 nt
	global_load_dwordx4 v[0:3], v[36:37], off offset:3072
	global_load_dwordx4 v[4:7], v[40:41], off offset:3072
	global_load_dwordx4 v[10:13], v[42:43], off offset:3072
	global_load_dwordx4 v[14:17], v[30:31], off offset:3072
	global_load_dwordx4 v[18:21], v[52:53], off
	global_load_dwordx4 v[22:25], v[38:39], off offset:3072
	global_load_dwordx4 v[78:81], v[54:55], off
	v_fma_f32 v95, -v156, v94, v157
	v_fmac_f32_e32 v94, v95, v158
	v_fma_f32 v95, -v156, v94, v157
	v_div_fmas_f32 v94, v95, v158, v94
	v_div_fixup_f32 v94, v94, v139, 1.0
	v_pk_mul_f32 v[8:9], v[8:9], v[94:95] op_sel_hi:[1,0]
	v_pk_mul_f32 v[82:83], v[82:83], v[94:95] op_sel_hi:[1,0]
	s_waitcnt vmcnt(12)
	v_lshlrev_b32_e32 v94, 16, v26
	v_and_b32_e32 v95, 0xffff0000, v26
	s_waitcnt vmcnt(11)
	v_lshlrev_b32_e32 v96, 16, v60
	v_and_b32_e32 v97, 0xffff0000, v60
	v_lshlrev_b32_e32 v60, 16, v61
	v_and_b32_e32 v61, 0xffff0000, v61
	v_lshlrev_b32_e32 v26, 16, v27
	v_and_b32_e32 v27, 0xffff0000, v27
	s_waitcnt vmcnt(9)
	v_lshlrev_b32_e32 v100, 16, v88
	v_and_b32_e32 v101, 0xffff0000, v88
	s_waitcnt vmcnt(8)
	v_lshlrev_b32_e32 v102, 16, v90
	v_and_b32_e32 v103, 0xffff0000, v90
	v_lshlrev_b32_e32 v90, 16, v91
	v_and_b32_e32 v91, 0xffff0000, v91
	s_waitcnt vmcnt(4)
	v_pk_fma_f32 v[4:5], v[4:5], v[82:83], v[10:11]
	v_pk_fma_f32 v[6:7], v[6:7], v[8:9], v[12:13]
	v_xor_b32_e32 v9, 0x80000000, v95
	v_xor_b32_e32 v8, 0x80000000, v94
	v_xor_b32_e32 v13, 0x80000000, v61
	v_xor_b32_e32 v12, 0x80000000, v60
	v_xor_b32_e32 v83, 0x80000000, v97
	v_xor_b32_e32 v82, 0x80000000, v96
	v_lshlrev_b32_e32 v88, 16, v89
	v_and_b32_e32 v89, 0xffff0000, v89
	v_xor_b32_e32 v11, 0x80000000, v27
	v_xor_b32_e32 v10, 0x80000000, v26
	v_pk_fma_f32 v[8:9], v[62:63], v[100:101], v[8:9] op_sel_hi:[0,1,1]
	v_pk_fma_f32 v[12:13], v[62:63], v[90:91], v[12:13] op_sel_hi:[0,1,1]
	v_pk_fma_f32 v[82:83], v[62:63], v[102:103], v[82:83] op_sel_hi:[0,1,1]
	v_pk_fma_f32 v[0:1], v[0:1], v[86:87], 1.0 op_sel_hi:[1,1,0]
	v_pk_fma_f32 v[2:3], v[2:3], v[84:85], 1.0 op_sel_hi:[1,1,0]
	v_pk_fma_f32 v[10:11], v[62:63], v[88:89], v[10:11] op_sel_hi:[0,1,1]
	s_waitcnt vmcnt(3)
	v_pk_fma_f32 v[8:9], v[14:15], v[8:9], v[94:95]
	s_waitcnt vmcnt(2)
	v_pk_fma_f32 v[14:15], v[18:19], v[82:83], v[96:97]
	v_pk_fma_f32 v[12:13], v[20:21], v[12:13], v[60:61]
	v_pk_fma_f32 v[10:11], v[16:17], v[10:11], v[26:27]
	v_pk_mul_f32 v[2:3], v[12:13], v[2:3]
	v_pk_mul_f32 v[0:1], v[14:15], v[0:1]
	v_pk_mul_f32 v[2:3], v[10:11], v[2:3]
	v_pk_mul_f32 v[0:1], v[8:9], v[0:1]
	s_waitcnt vmcnt(1)
	v_pk_mul_f32 v[2:3], v[24:25], v[2:3]
	v_pk_mul_f32 v[0:1], v[22:23], v[0:1]
	v_lshlrev_b32_e32 v98, 16, v66
	v_pk_mov_b32 v[8:9], v[0:1], v[2:3] op_sel:[1,0]
	v_mov_b32_e32 v1, v3
	v_pk_add_f32 v[0:1], v[8:9], v[0:1]
	v_and_b32_e32 v99, 0xffff0000, v66
	v_add_f32_e32 v0, v0, v1
	v_lshlrev_b32_e32 v66, 16, v67
	v_and_b32_e32 v67, 0xffff0000, v67
	v_add_f32_dpp v0, v0, v0 quad_perm:[1,0,3,2] row_mask:0xf bank_mask:0xf bound_ctrl:1
	v_lshlrev_b32_e32 v104, 16, v92
	v_and_b32_e32 v105, 0xffff0000, v92
	v_lshlrev_b32_e32 v92, 16, v93
	v_and_b32_e32 v93, 0xffff0000, v93
	v_xor_b32_e32 v85, 0x80000000, v67
	v_xor_b32_e32 v84, 0x80000000, v66
	v_xor_b32_e32 v87, 0x80000000, v99
	v_xor_b32_e32 v86, 0x80000000, v98
	v_add_f32_dpp v0, v0, v0 quad_perm:[2,3,0,1] row_mask:0xf bank_mask:0xf bound_ctrl:1
	v_pk_fma_f32 v[84:85], v[62:63], v[92:93], v[84:85] op_sel_hi:[0,1,1]
	v_pk_fma_f32 v[86:87], v[62:63], v[104:105], v[86:87] op_sel_hi:[0,1,1]
	v_add_f32_dpp v0, v0, v0 row_half_mirror row_mask:0xf bank_mask:0xf bound_ctrl:1
	s_waitcnt vmcnt(0)
	v_pk_fma_f32 v[16:17], v[78:79], v[86:87], v[98:99]
	v_pk_fma_f32 v[18:19], v[80:81], v[84:85], v[66:67]
	v_add_f32_dpp v0, v0, v0 row_mirror row_mask:0xf bank_mask:0xf bound_ctrl:1
	v_pk_fma_f32 v[2:3], v[18:19], v[0:1], v[6:7] op_sel_hi:[1,0,1]
	v_pk_fma_f32 v[0:1], v[16:17], v[0:1], v[4:5] op_sel_hi:[1,0,1]
	v_pk_mul_f32 v[2:3], v[2:3], v[70:71]
	v_pk_mul_f32 v[0:1], v[0:1], v[64:65]
	v_pk_fma_f32 v[2:3], v[2:3], v[72:73], v[76:77]
	v_pk_fma_f32 v[0:1], v[0:1], v[68:69], v[74:75]
	s_nop 0
	v_cvt_pk_bf16_f32 v0, v0, v1
	v_cvt_pk_bf16_f32 v1, v2, v3
	global_store_dwordx2 v[58:59], v[0:1], off offset:1536
	s_cbranch_scc0 .LBB0_1140
